# c14 plus first K-loop iteration peeled with C=0 MFMAs in all four GEMM phases (no per-tile accumulator clears)
# speedup vs baseline: 1.0176x; 1.0034x over previous
.LBB0_317:
	s_ashr_i32 s27, s26, 31
	s_lshl_b64 s[28:29], s[26:27], 20
	s_add_u32 s28, s42, s28
	s_addc_u32 s29, s43, s29
	s_and_b64 s[30:31], s[4:5], exec
	s_cselect_b32 s9, s29, s7
	s_cselect_b32 s27, s28, s6
	s_ashr_i32 s25, s24, 31
	s_lshl_b64 s[30:31], s[24:25], 20
	s_add_u32 s30, s44, s30
	s_addc_u32 s31, s45, s31
	s_and_b64 s[38:39], s[4:5], exec
	s_cselect_b32 s25, s31, s37
	s_cselect_b32 s62, s30, s36
	s_ashr_i32 s35, s34, 31
	s_lshl_b64 s[38:39], s[34:35], 13
	s_add_u32 s35, s36, 0x100
	v_mov_b32_e32 v179, v178
	v_mov_b32_e32 v178, v191
	v_mov_b32_e32 v191, v190
	v_mov_b32_e32 v190, v185
	v_mov_b32_e32 v185, v215
	v_mov_b32_e32 v203, v214
	v_lshl_add_u64 v[128:129], v[164:165], 0, s[38:39]
	v_lshl_add_u64 v[130:131], s[6:7], 0, v[170:171]
	s_nop 0
	v_lshl_add_u64 v[132:133], s[6:7], 0, v[172:173]
	s_addc_u32 s63, s37, 0
	s_mov_b32 s64, -2
	s_mov_b64 s[36:37], 0
	s_branch .Lpeel_p1

.Lpeel_p1:
	v_add_u32_e32 v146, s58, v176
	v_add_u32_e32 v150, s59, v176
	s_add_u32 s38, s6, s36
	ds_read_b128 v[134:137], v146
	ds_read_b128 v[138:141], v146 offset:1024
	ds_read_b128 v[142:145], v146 offset:2048
	ds_read_b128 v[146:149], v146 offset:3072
	ds_read_b128 v[204:207], v150
	ds_read_b128 v[208:211], v150 offset:1024
	ds_read_b128 v[212:215], v150 offset:2048
	ds_read_b128 v[216:219], v150 offset:3072
	s_addc_u32 s39, s7, s37
	s_add_u32 s38, s38, 0x100
	s_addc_u32 s39, s39, 0
	s_add_u32 s65, s35, s36
	s_addc_u32 s66, s63, s37
	s_cmpk_eq_i32 s36, 0xf00
	s_cselect_b32 s41, s9, s39
	s_cselect_b32 s40, s27, s38
	s_cselect_b32 s39, s25, s66
	s_cselect_b32 s38, s62, s65
	v_lshl_add_u64 v[150:151], v[130:131], 0, s[36:37]
	s_add_i32 m0, s47, 0xc000
	ds_read_b128 v[220:223], v201
	ds_read_b128 v[224:227], v201 offset:1024
	ds_read_b128 v[228:231], v201 offset:2048
	ds_read_b128 v[232:235], v201 offset:3072
	ds_read_b128 v[236:239], v201 offset:4096
	ds_read_b128 v[240:243], v201 offset:5120
	ds_read_b128 v[244:247], v201 offset:6144
	ds_read_b128 v[248:251], v201 offset:7168
	global_load_lds_dwordx4 v[150:151], off
	v_lshl_add_u64 v[150:151], v[132:133], 0, s[36:37]
	s_add_i32 m0, s47, 0xe000
	s_nop 0
	global_load_lds_dwordx4 v[150:151], off
	s_waitcnt vmcnt(8)
	s_waitcnt lgkmcnt(0)
	s_barrier
	s_setprio 1
	s_waitcnt lgkmcnt(0)
	v_mfma_f32_16x16x32_bf16 v[124:127], v[134:137], v[220:223], 0
	v_mfma_f32_16x16x32_bf16 v[120:123], v[142:145], v[220:223], 0
	v_mfma_f32_16x16x32_bf16 v[108:111], v[134:137], v[228:231], 0
	v_mfma_f32_16x16x32_bf16 v[96:99], v[142:145], v[228:231], 0
	v_mfma_f32_16x16x32_bf16 v[92:95], v[134:137], v[236:239], 0
	v_mfma_f32_16x16x32_bf16 v[80:83], v[142:145], v[236:239], 0
	v_mfma_f32_16x16x32_bf16 v[76:79], v[134:137], v[244:247], 0
	v_mfma_f32_16x16x32_bf16 v[64:67], v[142:145], v[244:247], 0
	v_mfma_f32_16x16x32_bf16 v[124:127], v[138:141], v[224:227], v[124:127]
	v_mfma_f32_16x16x32_bf16 v[120:123], v[146:149], v[224:227], v[120:123]
	v_mfma_f32_16x16x32_bf16 v[108:111], v[138:141], v[232:235], v[108:111]
	v_mfma_f32_16x16x32_bf16 v[96:99], v[146:149], v[232:235], v[96:99]
	v_mfma_f32_16x16x32_bf16 v[92:95], v[138:141], v[240:243], v[92:95]
	v_mfma_f32_16x16x32_bf16 v[80:83], v[146:149], v[240:243], v[80:83]
	v_mfma_f32_16x16x32_bf16 v[76:79], v[138:141], v[248:251], v[76:79]
	v_mfma_f32_16x16x32_bf16 v[64:67], v[146:149], v[248:251], v[64:67]
	s_setprio 0
	s_setprio 1
	v_mfma_f32_16x16x32_bf16 v[104:107], v[204:207], v[220:223], 0
	v_mfma_f32_16x16x32_bf16 v[100:103], v[212:215], v[220:223], 0
	v_mfma_f32_16x16x32_bf16 v[88:91], v[204:207], v[228:231], 0
	v_mfma_f32_16x16x32_bf16 v[84:87], v[212:215], v[228:231], 0
	v_mfma_f32_16x16x32_bf16 v[72:75], v[204:207], v[236:239], 0
	v_mfma_f32_16x16x32_bf16 v[68:71], v[212:215], v[236:239], 0
	v_mfma_f32_16x16x32_bf16 v[60:63], v[204:207], v[244:247], 0
	v_mfma_f32_16x16x32_bf16 v[56:59], v[212:215], v[244:247], 0
	v_mfma_f32_16x16x32_bf16 v[104:107], v[208:211], v[224:227], v[104:107]
	v_mfma_f32_16x16x32_bf16 v[100:103], v[216:219], v[224:227], v[100:103]
	v_mfma_f32_16x16x32_bf16 v[88:91], v[208:211], v[232:235], v[88:91]
	v_mfma_f32_16x16x32_bf16 v[84:87], v[216:219], v[232:235], v[84:87]
	v_mfma_f32_16x16x32_bf16 v[72:75], v[208:211], v[240:243], v[72:75]
	v_mfma_f32_16x16x32_bf16 v[68:71], v[216:219], v[240:243], v[68:71]
	v_mfma_f32_16x16x32_bf16 v[60:63], v[208:211], v[248:251], v[60:63]
	v_mfma_f32_16x16x32_bf16 v[56:59], v[216:219], v[248:251], v[56:59]
	s_setprio 0
	s_barrier
	s_add_i32 s65, s58, s46
	v_lshl_add_u64 v[150:151], s[38:39], 0, v[154:155]
	s_mov_b32 m0, s65
	ds_read_b128 v[220:223], v201 offset:16384
	ds_read_b128 v[224:227], v201 offset:17408
	ds_read_b128 v[228:231], v201 offset:18432
	ds_read_b128 v[232:235], v201 offset:19456
	ds_read_b128 v[236:239], v201 offset:20480
	ds_read_b128 v[240:243], v201 offset:21504
	ds_read_b128 v[244:247], v201 offset:22528
	ds_read_b128 v[248:251], v201 offset:23552
	global_load_lds_dwordx4 v[150:151], off
	s_add_i32 m0, s65, 0x2000
	s_add_u32 s66, s38, 0x80000
	v_lshl_add_u64 v[174:175], s[38:39], 0, v[158:159]
	s_addc_u32 s67, s39, 0
	s_add_i32 s65, s59, s46
	global_load_lds_dwordx4 v[174:175], off
	v_lshl_add_u64 v[252:253], s[66:67], 0, v[154:155]
	s_mov_b32 m0, s65
	v_lshl_add_u64 v[186:187], s[40:41], 0, v[156:157]
	global_load_lds_dwordx4 v[252:253], off
	v_lshl_add_u64 v[252:253], s[66:67], 0, v[158:159]
	s_add_i32 m0, s65, 0x2000
	s_nop 0
	global_load_lds_dwordx4 v[252:253], off
	v_lshl_add_u64 v[252:253], s[40:41], 0, v[152:153]
	s_mov_b32 m0, s47
	s_nop 0
	global_load_lds_dwordx4 v[252:253], off
	s_mov_b32 m0, s48
	s_nop 0
	global_load_lds_dwordx4 v[186:187], off
	s_waitcnt vmcnt(8)
	s_waitcnt lgkmcnt(0)
	s_barrier
	s_setprio 1
	s_waitcnt lgkmcnt(0)
	v_mfma_f32_16x16x32_bf16 v[52:55], v[134:137], v[220:223], 0
	v_mfma_f32_16x16x32_bf16 v[48:51], v[142:145], v[220:223], 0
	v_mfma_f32_16x16x32_bf16 v[44:47], v[134:137], v[228:231], 0
	v_mfma_f32_16x16x32_bf16 v[32:35], v[142:145], v[228:231], 0
	v_mfma_f32_16x16x32_bf16 v[28:31], v[134:137], v[236:239], 0
	v_mfma_f32_16x16x32_bf16 v[16:19], v[142:145], v[236:239], 0
	v_mfma_f32_16x16x32_bf16 v[116:119], v[134:137], v[244:247], 0
	v_mfma_f32_16x16x32_bf16 v[112:115], v[142:145], v[244:247], 0
	v_mfma_f32_16x16x32_bf16 v[52:55], v[138:141], v[224:227], v[52:55]
	v_mfma_f32_16x16x32_bf16 v[48:51], v[146:149], v[224:227], v[48:51]
	v_mfma_f32_16x16x32_bf16 v[44:47], v[138:141], v[232:235], v[44:47]
	v_mfma_f32_16x16x32_bf16 v[32:35], v[146:149], v[232:235], v[32:35]
	v_mfma_f32_16x16x32_bf16 v[28:31], v[138:141], v[240:243], v[28:31]
	v_mfma_f32_16x16x32_bf16 v[16:19], v[146:149], v[240:243], v[16:19]
	v_mfma_f32_16x16x32_bf16 v[116:119], v[138:141], v[248:251], v[116:119]
	v_mfma_f32_16x16x32_bf16 v[112:115], v[146:149], v[248:251], v[112:115]
	s_setprio 0
	s_setprio 1
	v_mfma_f32_16x16x32_bf16 v[40:43], v[204:207], v[220:223], 0
	v_mfma_f32_16x16x32_bf16 v[36:39], v[212:215], v[220:223], 0
	v_mfma_f32_16x16x32_bf16 v[24:27], v[204:207], v[228:231], 0
	v_mfma_f32_16x16x32_bf16 v[20:23], v[212:215], v[228:231], 0
	v_mfma_f32_16x16x32_bf16 v[12:15], v[204:207], v[236:239], 0
	v_mfma_f32_16x16x32_bf16 v[8:11], v[212:215], v[236:239], 0
	v_mfma_f32_16x16x32_bf16 v[4:7], v[204:207], v[244:247], 0
	v_mfma_f32_16x16x32_bf16 v[0:3], v[212:215], v[244:247], 0
	v_mfma_f32_16x16x32_bf16 v[40:43], v[208:211], v[224:227], v[40:43]
	v_mfma_f32_16x16x32_bf16 v[36:39], v[216:219], v[224:227], v[36:39]
	v_mfma_f32_16x16x32_bf16 v[24:27], v[208:211], v[232:235], v[24:27]
	v_mfma_f32_16x16x32_bf16 v[20:23], v[216:219], v[232:235], v[20:23]
	v_mfma_f32_16x16x32_bf16 v[12:15], v[208:211], v[240:243], v[12:15]
	v_mfma_f32_16x16x32_bf16 v[8:11], v[216:219], v[240:243], v[8:11]
	v_mfma_f32_16x16x32_bf16 v[4:7], v[208:211], v[248:251], v[4:7]
	v_mfma_f32_16x16x32_bf16 v[0:3], v[216:219], v[248:251], v[0:3]
	s_setprio 0
	s_barrier
	s_add_i32 s65, 0, 0x18000
	s_add_i32 s66, 0, 0x1c000
	v_add_u32_e32 v146, s65, v176
	v_add_u32_e32 v160, s66, v176
	ds_read_b128 v[134:137], v146
	ds_read_b128 v[138:141], v146 offset:1024
	ds_read_b128 v[142:145], v146 offset:2048
	ds_read_b128 v[146:149], v146 offset:3072
	ds_read_b128 v[204:207], v160
	ds_read_b128 v[208:211], v160 offset:1024
	ds_read_b128 v[212:215], v160 offset:2048
	ds_read_b128 v[216:219], v160 offset:3072
	s_add_u32 s40, s40, 0x80000
	s_addc_u32 s41, s41, 0
	s_mov_b32 m0, s49
	v_lshl_add_u64 v[188:189], s[40:41], 0, v[152:153]
	ds_read_b128 v[220:223], v201 offset:32768
	ds_read_b128 v[224:227], v201 offset:33792
	ds_read_b128 v[228:231], v201 offset:34816
	ds_read_b128 v[232:235], v201 offset:35840
	ds_read_b128 v[236:239], v201 offset:36864
	ds_read_b128 v[240:243], v201 offset:37888
	ds_read_b128 v[244:247], v201 offset:38912
	ds_read_b128 v[248:251], v201 offset:39936
	global_load_lds_dwordx4 v[188:189], off
	v_lshl_add_u64 v[188:189], s[40:41], 0, v[156:157]
	s_mov_b32 m0, s50
	s_nop 0
	global_load_lds_dwordx4 v[188:189], off
	s_waitcnt vmcnt(8)
	s_waitcnt lgkmcnt(0)
	s_barrier
	s_setprio 1
	s_waitcnt lgkmcnt(0)
	v_mfma_f32_16x16x32_bf16 v[124:127], v[134:137], v[220:223], v[124:127]
	v_mfma_f32_16x16x32_bf16 v[120:123], v[142:145], v[220:223], v[120:123]
	v_mfma_f32_16x16x32_bf16 v[108:111], v[134:137], v[228:231], v[108:111]
	v_mfma_f32_16x16x32_bf16 v[96:99], v[142:145], v[228:231], v[96:99]
	v_mfma_f32_16x16x32_bf16 v[92:95], v[134:137], v[236:239], v[92:95]
	v_mfma_f32_16x16x32_bf16 v[80:83], v[142:145], v[236:239], v[80:83]
	v_mfma_f32_16x16x32_bf16 v[76:79], v[134:137], v[244:247], v[76:79]
	v_mfma_f32_16x16x32_bf16 v[64:67], v[142:145], v[244:247], v[64:67]
	v_mfma_f32_16x16x32_bf16 v[124:127], v[138:141], v[224:227], v[124:127]
	v_mfma_f32_16x16x32_bf16 v[120:123], v[146:149], v[224:227], v[120:123]
	v_mfma_f32_16x16x32_bf16 v[108:111], v[138:141], v[232:235], v[108:111]
	v_mfma_f32_16x16x32_bf16 v[96:99], v[146:149], v[232:235], v[96:99]
	v_mfma_f32_16x16x32_bf16 v[92:95], v[138:141], v[240:243], v[92:95]
	v_mfma_f32_16x16x32_bf16 v[80:83], v[146:149], v[240:243], v[80:83]
	v_mfma_f32_16x16x32_bf16 v[76:79], v[138:141], v[248:251], v[76:79]
	v_mfma_f32_16x16x32_bf16 v[64:67], v[146:149], v[248:251], v[64:67]
	s_setprio 0
	s_setprio 1
	v_mfma_f32_16x16x32_bf16 v[104:107], v[204:207], v[220:223], v[104:107]
	v_mfma_f32_16x16x32_bf16 v[100:103], v[212:215], v[220:223], v[100:103]
	v_mfma_f32_16x16x32_bf16 v[88:91], v[204:207], v[228:231], v[88:91]
	v_mfma_f32_16x16x32_bf16 v[84:87], v[212:215], v[228:231], v[84:87]
	v_mfma_f32_16x16x32_bf16 v[72:75], v[204:207], v[236:239], v[72:75]
	v_mfma_f32_16x16x32_bf16 v[68:71], v[212:215], v[236:239], v[68:71]
	v_mfma_f32_16x16x32_bf16 v[60:63], v[204:207], v[244:247], v[60:63]
	v_mfma_f32_16x16x32_bf16 v[56:59], v[212:215], v[244:247], v[56:59]
	v_mfma_f32_16x16x32_bf16 v[104:107], v[208:211], v[224:227], v[104:107]
	v_mfma_f32_16x16x32_bf16 v[100:103], v[216:219], v[224:227], v[100:103]
	v_mfma_f32_16x16x32_bf16 v[88:91], v[208:211], v[232:235], v[88:91]
	v_mfma_f32_16x16x32_bf16 v[84:87], v[216:219], v[232:235], v[84:87]
	v_mfma_f32_16x16x32_bf16 v[72:75], v[208:211], v[240:243], v[72:75]
	v_mfma_f32_16x16x32_bf16 v[68:71], v[216:219], v[240:243], v[68:71]
	v_mfma_f32_16x16x32_bf16 v[60:63], v[208:211], v[248:251], v[60:63]
	v_mfma_f32_16x16x32_bf16 v[56:59], v[216:219], v[248:251], v[56:59]
	s_setprio 0
	s_barrier
	s_add_i32 s40, s65, s46
	v_lshl_add_u64 v[150:151], v[150:151], 0, s[18:19]
	s_mov_b32 m0, s40
	ds_read_b128 v[220:223], v201 offset:49152
	ds_read_b128 v[224:227], v201 offset:50176
	ds_read_b128 v[228:231], v201 offset:51200
	ds_read_b128 v[232:235], v201 offset:52224
	ds_read_b128 v[236:239], v201 offset:53248
	ds_read_b128 v[240:243], v201 offset:54272
	ds_read_b128 v[244:247], v201 offset:55296
	ds_read_b128 v[248:251], v201 offset:56320
	global_load_lds_dwordx4 v[150:151], off
	s_add_i32 m0, s40, 0x2000
	s_add_u32 s38, s38, 0x80080
	v_lshl_add_u64 v[150:151], v[174:175], 0, s[18:19]
	s_addc_u32 s39, s39, 0
	s_add_i32 s40, s66, s46
	global_load_lds_dwordx4 v[150:151], off
	v_lshl_add_u64 v[150:151], s[38:39], 0, v[154:155]
	s_mov_b32 m0, s40
	s_nop 0
	global_load_lds_dwordx4 v[150:151], off
	v_lshl_add_u64 v[150:151], s[38:39], 0, v[158:159]
	s_add_i32 m0, s40, 0x2000
	s_nop 0
	global_load_lds_dwordx4 v[150:151], off
	v_lshl_add_u64 v[150:151], v[252:253], 0, s[18:19]
	s_mov_b32 m0, s53
	s_nop 0
	global_load_lds_dwordx4 v[150:151], off
	v_lshl_add_u64 v[150:151], v[186:187], 0, s[18:19]
	s_mov_b32 m0, s54
	s_nop 0
	global_load_lds_dwordx4 v[150:151], off
	s_waitcnt vmcnt(8)
	s_waitcnt lgkmcnt(0)
	s_barrier
	s_setprio 1
	s_waitcnt lgkmcnt(0)
	v_mfma_f32_16x16x32_bf16 v[52:55], v[134:137], v[220:223], v[52:55]
	v_mfma_f32_16x16x32_bf16 v[48:51], v[142:145], v[220:223], v[48:51]
	v_mfma_f32_16x16x32_bf16 v[44:47], v[134:137], v[228:231], v[44:47]
	v_mfma_f32_16x16x32_bf16 v[32:35], v[142:145], v[228:231], v[32:35]
	v_mfma_f32_16x16x32_bf16 v[28:31], v[134:137], v[236:239], v[28:31]
	v_mfma_f32_16x16x32_bf16 v[16:19], v[142:145], v[236:239], v[16:19]
	v_mfma_f32_16x16x32_bf16 v[116:119], v[134:137], v[244:247], v[116:119]
	v_mfma_f32_16x16x32_bf16 v[112:115], v[142:145], v[244:247], v[112:115]
	v_mfma_f32_16x16x32_bf16 v[52:55], v[138:141], v[224:227], v[52:55]
	v_mfma_f32_16x16x32_bf16 v[48:51], v[146:149], v[224:227], v[48:51]
	v_mfma_f32_16x16x32_bf16 v[44:47], v[138:141], v[232:235], v[44:47]
	v_mfma_f32_16x16x32_bf16 v[32:35], v[146:149], v[232:235], v[32:35]
	v_mfma_f32_16x16x32_bf16 v[28:31], v[138:141], v[240:243], v[28:31]
	v_mfma_f32_16x16x32_bf16 v[16:19], v[146:149], v[240:243], v[16:19]
	v_mfma_f32_16x16x32_bf16 v[116:119], v[138:141], v[248:251], v[116:119]
	v_mfma_f32_16x16x32_bf16 v[112:115], v[146:149], v[248:251], v[112:115]
	s_setprio 0
	s_setprio 1
	v_mfma_f32_16x16x32_bf16 v[40:43], v[204:207], v[220:223], v[40:43]
	v_mfma_f32_16x16x32_bf16 v[36:39], v[212:215], v[220:223], v[36:39]
	v_mfma_f32_16x16x32_bf16 v[24:27], v[204:207], v[228:231], v[24:27]
	v_mfma_f32_16x16x32_bf16 v[20:23], v[212:215], v[228:231], v[20:23]
	v_mfma_f32_16x16x32_bf16 v[12:15], v[204:207], v[236:239], v[12:15]
	v_mfma_f32_16x16x32_bf16 v[8:11], v[212:215], v[236:239], v[8:11]
	v_mfma_f32_16x16x32_bf16 v[4:7], v[204:207], v[244:247], v[4:7]
	v_mfma_f32_16x16x32_bf16 v[0:3], v[212:215], v[244:247], v[0:3]
	v_mfma_f32_16x16x32_bf16 v[40:43], v[208:211], v[224:227], v[40:43]
	v_mfma_f32_16x16x32_bf16 v[36:39], v[216:219], v[224:227], v[36:39]
	v_mfma_f32_16x16x32_bf16 v[24:27], v[208:211], v[232:235], v[24:27]
	v_mfma_f32_16x16x32_bf16 v[20:23], v[216:219], v[232:235], v[20:23]
	v_mfma_f32_16x16x32_bf16 v[12:15], v[208:211], v[240:243], v[12:15]
	v_mfma_f32_16x16x32_bf16 v[8:11], v[216:219], v[240:243], v[8:11]
	v_mfma_f32_16x16x32_bf16 v[4:7], v[208:211], v[248:251], v[4:7]
	v_mfma_f32_16x16x32_bf16 v[0:3], v[216:219], v[248:251], v[0:3]
	s_setprio 0
	s_barrier
	s_add_i32 s64, s64, 2
	s_add_u32 s36, s36, 0x100
	s_addc_u32 s37, s37, 0
	s_cmp_gt_u32 s64, 29
	s_cbranch_scc1 .LBB0_321
	s_branch .LBB0_319
	s_nop 0

.LBB0_883:
	s_ashr_i32 s19, s18, 31
	s_lshl_b64 s[20:21], s[18:19], 20
	s_add_u32 s20, s34, s20
	s_addc_u32 s21, s35, s21
	s_and_b64 s[22:23], s[4:5], exec
	s_cselect_b32 s7, s21, s27
	s_cselect_b32 s19, s20, s26
	s_ashr_i32 s17, s16, 31
	s_lshl_b64 s[22:23], s[16:17], 20
	s_add_u32 s22, s36, s22
	s_addc_u32 s23, s37, s23
	s_and_b64 s[30:31], s[4:5], exec
	s_cselect_b32 s17, s23, s29
	s_cselect_b32 s25, s22, s28
	s_add_u32 s26, s26, 0x80080
	s_addc_u32 s27, s27, 0
	s_add_u32 s52, s28, 0x100
	s_addc_u32 s53, s29, 0
	s_mov_b32 s54, -2
	ds_read_b128 v[144:147], v174
	ds_read_b128 v[178:181], v174 offset:1024
	ds_read_b128 v[182:185], v174 offset:2048
	ds_read_b128 v[186:189], v174 offset:3072
	ds_read_b128 v[190:193], v175
	ds_read_b128 v[194:197], v175 offset:1024
	ds_read_b128 v[198:201], v175 offset:2048
	ds_read_b128 v[202:205], v175 offset:3072
	s_add_u32 s28, s26, 0xfff80080
	s_addc_u32 s29, s27, -1
	s_cmp_eq_u32 s54, 28
	s_cselect_b32 s31, s7, s29
	s_cselect_b32 s30, s19, s28
	s_cselect_b32 s29, s17, s53
	s_cselect_b32 s28, s25, s52
	v_lshl_add_u64 v[238:239], s[26:27], 0, v[136:137]
	s_add_i32 m0, s39, 0xc000
	ds_read_b128 v[206:209], v176
	ds_read_b128 v[210:213], v176 offset:1024
	ds_read_b128 v[214:217], v176 offset:2048
	ds_read_b128 v[218:221], v176 offset:3072
	ds_read_b128 v[222:225], v176 offset:4096
	ds_read_b128 v[226:229], v176 offset:5120
	ds_read_b128 v[230:233], v176 offset:6144
	ds_read_b128 v[234:237], v176 offset:7168
	global_load_lds_dwordx4 v[238:239], off
	v_lshl_add_u64 v[238:239], s[26:27], 0, v[138:139]
	s_add_i32 m0, s39, 0xe000
	s_nop 0
	global_load_lds_dwordx4 v[238:239], off
	s_waitcnt vmcnt(8)
	s_waitcnt lgkmcnt(0)
	s_barrier
	s_setprio 1
	s_waitcnt lgkmcnt(0)
	v_mfma_f32_16x16x32_bf16 v[124:127], v[144:147], v[206:209], 0
	v_mfma_f32_16x16x32_bf16 v[120:123], v[182:185], v[206:209], 0
	v_mfma_f32_16x16x32_bf16 v[108:111], v[144:147], v[214:217], 0
	v_mfma_f32_16x16x32_bf16 v[104:107], v[182:185], v[214:217], 0
	v_mfma_f32_16x16x32_bf16 v[92:95], v[144:147], v[222:225], 0
	v_mfma_f32_16x16x32_bf16 v[88:91], v[182:185], v[222:225], 0
	v_mfma_f32_16x16x32_bf16 v[76:79], v[144:147], v[230:233], 0
	v_mfma_f32_16x16x32_bf16 v[72:75], v[182:185], v[230:233], 0
	v_mfma_f32_16x16x32_bf16 v[124:127], v[178:181], v[210:213], v[124:127]
	v_mfma_f32_16x16x32_bf16 v[120:123], v[186:189], v[210:213], v[120:123]
	v_mfma_f32_16x16x32_bf16 v[108:111], v[178:181], v[218:221], v[108:111]
	v_mfma_f32_16x16x32_bf16 v[104:107], v[186:189], v[218:221], v[104:107]
	v_mfma_f32_16x16x32_bf16 v[92:95], v[178:181], v[226:229], v[92:95]
	v_mfma_f32_16x16x32_bf16 v[88:91], v[186:189], v[226:229], v[88:91]
	v_mfma_f32_16x16x32_bf16 v[76:79], v[178:181], v[234:237], v[76:79]
	v_mfma_f32_16x16x32_bf16 v[72:75], v[186:189], v[234:237], v[72:75]
	s_setprio 0
	s_setprio 1
	v_mfma_f32_16x16x32_bf16 v[116:119], v[190:193], v[206:209], 0
	v_mfma_f32_16x16x32_bf16 v[112:115], v[198:201], v[206:209], 0
	v_mfma_f32_16x16x32_bf16 v[100:103], v[190:193], v[214:217], 0
	v_mfma_f32_16x16x32_bf16 v[96:99], v[198:201], v[214:217], 0
	v_mfma_f32_16x16x32_bf16 v[84:87], v[190:193], v[222:225], 0
	v_mfma_f32_16x16x32_bf16 v[80:83], v[198:201], v[222:225], 0
	v_mfma_f32_16x16x32_bf16 v[68:71], v[190:193], v[230:233], 0
	v_mfma_f32_16x16x32_bf16 v[64:67], v[198:201], v[230:233], 0
	v_mfma_f32_16x16x32_bf16 v[116:119], v[194:197], v[210:213], v[116:119]
	v_mfma_f32_16x16x32_bf16 v[112:115], v[202:205], v[210:213], v[112:115]
	v_mfma_f32_16x16x32_bf16 v[100:103], v[194:197], v[218:221], v[100:103]
	v_mfma_f32_16x16x32_bf16 v[96:99], v[202:205], v[218:221], v[96:99]
	v_mfma_f32_16x16x32_bf16 v[84:87], v[194:197], v[226:229], v[84:87]
	v_mfma_f32_16x16x32_bf16 v[80:83], v[202:205], v[226:229], v[80:83]
	v_mfma_f32_16x16x32_bf16 v[68:71], v[194:197], v[234:237], v[68:71]
	v_mfma_f32_16x16x32_bf16 v[64:67], v[202:205], v[234:237], v[64:67]
	s_setprio 0
	s_barrier
	s_add_i32 s55, s50, s38
	v_lshl_add_u64 v[238:239], s[28:29], 0, v[130:131]
	s_mov_b32 m0, s55
	ds_read_b128 v[206:209], v176 offset:16384
	ds_read_b128 v[210:213], v176 offset:17408
	ds_read_b128 v[214:217], v176 offset:18432
	ds_read_b128 v[218:221], v176 offset:19456
	ds_read_b128 v[222:225], v176 offset:20480
	ds_read_b128 v[226:229], v176 offset:21504
	ds_read_b128 v[230:233], v176 offset:22528
	ds_read_b128 v[234:237], v176 offset:23552
	global_load_lds_dwordx4 v[238:239], off
	s_add_i32 m0, s55, 0x2000
	s_add_u32 s56, s28, 0x80000
	v_lshl_add_u64 v[240:241], s[28:29], 0, v[134:135]
	s_addc_u32 s57, s29, 0
	s_add_i32 s55, s51, s38
	global_load_lds_dwordx4 v[240:241], off
	v_lshl_add_u64 v[242:243], s[56:57], 0, v[130:131]
	s_mov_b32 m0, s55
	v_lshl_add_u64 v[244:245], s[30:31], 0, v[132:133]
	global_load_lds_dwordx4 v[242:243], off
	v_lshl_add_u64 v[242:243], s[56:57], 0, v[134:135]
	s_add_i32 m0, s55, 0x2000
	s_nop 0
	global_load_lds_dwordx4 v[242:243], off
	v_lshl_add_u64 v[242:243], s[30:31], 0, v[128:129]
	s_mov_b32 m0, s39
	s_nop 0
	global_load_lds_dwordx4 v[242:243], off
	s_mov_b32 m0, s40
	s_nop 0
	global_load_lds_dwordx4 v[244:245], off
	s_waitcnt vmcnt(8)
	s_waitcnt lgkmcnt(0)
	s_barrier
	s_setprio 1
	s_waitcnt lgkmcnt(0)
	v_mfma_f32_16x16x32_bf16 v[60:63], v[144:147], v[206:209], 0
	v_mfma_f32_16x16x32_bf16 v[56:59], v[182:185], v[206:209], 0
	v_mfma_f32_16x16x32_bf16 v[44:47], v[144:147], v[214:217], 0
	v_mfma_f32_16x16x32_bf16 v[40:43], v[182:185], v[214:217], 0
	v_mfma_f32_16x16x32_bf16 v[28:31], v[144:147], v[222:225], 0
	v_mfma_f32_16x16x32_bf16 v[24:27], v[182:185], v[222:225], 0
	v_mfma_f32_16x16x32_bf16 v[12:15], v[144:147], v[230:233], 0
	v_mfma_f32_16x16x32_bf16 v[8:11], v[182:185], v[230:233], 0
	v_mfma_f32_16x16x32_bf16 v[60:63], v[178:181], v[210:213], v[60:63]
	v_mfma_f32_16x16x32_bf16 v[56:59], v[186:189], v[210:213], v[56:59]
	v_mfma_f32_16x16x32_bf16 v[44:47], v[178:181], v[218:221], v[44:47]
	v_mfma_f32_16x16x32_bf16 v[40:43], v[186:189], v[218:221], v[40:43]
	v_mfma_f32_16x16x32_bf16 v[28:31], v[178:181], v[226:229], v[28:31]
	v_mfma_f32_16x16x32_bf16 v[24:27], v[186:189], v[226:229], v[24:27]
	v_mfma_f32_16x16x32_bf16 v[12:15], v[178:181], v[234:237], v[12:15]
	v_mfma_f32_16x16x32_bf16 v[8:11], v[186:189], v[234:237], v[8:11]
	s_setprio 0
	s_setprio 1
	v_mfma_f32_16x16x32_bf16 v[52:55], v[190:193], v[206:209], 0
	v_mfma_f32_16x16x32_bf16 v[48:51], v[198:201], v[206:209], 0
	v_mfma_f32_16x16x32_bf16 v[36:39], v[190:193], v[214:217], 0
	v_mfma_f32_16x16x32_bf16 v[32:35], v[198:201], v[214:217], 0
	v_mfma_f32_16x16x32_bf16 v[20:23], v[190:193], v[222:225], 0
	v_mfma_f32_16x16x32_bf16 v[16:19], v[198:201], v[222:225], 0
	v_mfma_f32_16x16x32_bf16 v[4:7], v[190:193], v[230:233], 0
	v_mfma_f32_16x16x32_bf16 v[0:3], v[198:201], v[230:233], 0
	v_mfma_f32_16x16x32_bf16 v[52:55], v[194:197], v[210:213], v[52:55]
	v_mfma_f32_16x16x32_bf16 v[48:51], v[202:205], v[210:213], v[48:51]
	v_mfma_f32_16x16x32_bf16 v[36:39], v[194:197], v[218:221], v[36:39]
	v_mfma_f32_16x16x32_bf16 v[32:35], v[202:205], v[218:221], v[32:35]
	v_mfma_f32_16x16x32_bf16 v[20:23], v[194:197], v[226:229], v[20:23]
	v_mfma_f32_16x16x32_bf16 v[16:19], v[202:205], v[226:229], v[16:19]
	v_mfma_f32_16x16x32_bf16 v[4:7], v[194:197], v[234:237], v[4:7]
	v_mfma_f32_16x16x32_bf16 v[0:3], v[202:205], v[234:237], v[0:3]
	s_setprio 0
	s_barrier
	s_add_i32 s55, 0, 0x18000
	v_add_u32_e32 v177, s55, v149
	s_add_i32 s56, 0, 0x1c000
	ds_read_b128 v[144:147], v177
	ds_read_b128 v[178:181], v177 offset:1024
	ds_read_b128 v[182:185], v177 offset:2048
	ds_read_b128 v[186:189], v177 offset:3072
	v_add_u32_e32 v177, s56, v149
	ds_read_b128 v[190:193], v177
	ds_read_b128 v[194:197], v177 offset:1024
	ds_read_b128 v[198:201], v177 offset:2048
	ds_read_b128 v[202:205], v177 offset:3072
	s_add_u32 s30, s30, 0x80000
	s_addc_u32 s31, s31, 0
	s_mov_b32 m0, s41
	v_lshl_add_u64 v[246:247], s[30:31], 0, v[128:129]
	ds_read_b128 v[206:209], v176 offset:32768
	ds_read_b128 v[210:213], v176 offset:33792
	ds_read_b128 v[214:217], v176 offset:34816
	ds_read_b128 v[218:221], v176 offset:35840
	ds_read_b128 v[222:225], v176 offset:36864
	ds_read_b128 v[226:229], v176 offset:37888
	ds_read_b128 v[230:233], v176 offset:38912
	ds_read_b128 v[234:237], v176 offset:39936
	global_load_lds_dwordx4 v[246:247], off
	v_lshl_add_u64 v[246:247], s[30:31], 0, v[132:133]
	s_mov_b32 m0, s42
	s_nop 0
	global_load_lds_dwordx4 v[246:247], off
	s_waitcnt vmcnt(8)
	s_waitcnt lgkmcnt(0)
	s_barrier
	s_setprio 1
	s_waitcnt lgkmcnt(0)
	v_mfma_f32_16x16x32_bf16 v[124:127], v[144:147], v[206:209], v[124:127]
	v_mfma_f32_16x16x32_bf16 v[120:123], v[182:185], v[206:209], v[120:123]
	v_mfma_f32_16x16x32_bf16 v[108:111], v[144:147], v[214:217], v[108:111]
	v_mfma_f32_16x16x32_bf16 v[104:107], v[182:185], v[214:217], v[104:107]
	v_mfma_f32_16x16x32_bf16 v[92:95], v[144:147], v[222:225], v[92:95]
	v_mfma_f32_16x16x32_bf16 v[88:91], v[182:185], v[222:225], v[88:91]
	v_mfma_f32_16x16x32_bf16 v[76:79], v[144:147], v[230:233], v[76:79]
	v_mfma_f32_16x16x32_bf16 v[72:75], v[182:185], v[230:233], v[72:75]
	v_mfma_f32_16x16x32_bf16 v[124:127], v[178:181], v[210:213], v[124:127]
	v_mfma_f32_16x16x32_bf16 v[120:123], v[186:189], v[210:213], v[120:123]
	v_mfma_f32_16x16x32_bf16 v[108:111], v[178:181], v[218:221], v[108:111]
	v_mfma_f32_16x16x32_bf16 v[104:107], v[186:189], v[218:221], v[104:107]
	v_mfma_f32_16x16x32_bf16 v[92:95], v[178:181], v[226:229], v[92:95]
	v_mfma_f32_16x16x32_bf16 v[88:91], v[186:189], v[226:229], v[88:91]
	v_mfma_f32_16x16x32_bf16 v[76:79], v[178:181], v[234:237], v[76:79]
	v_mfma_f32_16x16x32_bf16 v[72:75], v[186:189], v[234:237], v[72:75]
	s_setprio 0
	s_setprio 1
	v_mfma_f32_16x16x32_bf16 v[116:119], v[190:193], v[206:209], v[116:119]
	v_mfma_f32_16x16x32_bf16 v[112:115], v[198:201], v[206:209], v[112:115]
	v_mfma_f32_16x16x32_bf16 v[100:103], v[190:193], v[214:217], v[100:103]
	v_mfma_f32_16x16x32_bf16 v[96:99], v[198:201], v[214:217], v[96:99]
	v_mfma_f32_16x16x32_bf16 v[84:87], v[190:193], v[222:225], v[84:87]
	v_mfma_f32_16x16x32_bf16 v[80:83], v[198:201], v[222:225], v[80:83]
	v_mfma_f32_16x16x32_bf16 v[68:71], v[190:193], v[230:233], v[68:71]
	v_mfma_f32_16x16x32_bf16 v[64:67], v[198:201], v[230:233], v[64:67]
	v_mfma_f32_16x16x32_bf16 v[116:119], v[194:197], v[210:213], v[116:119]
	v_mfma_f32_16x16x32_bf16 v[112:115], v[202:205], v[210:213], v[112:115]
	v_mfma_f32_16x16x32_bf16 v[100:103], v[194:197], v[218:221], v[100:103]
	v_mfma_f32_16x16x32_bf16 v[96:99], v[202:205], v[218:221], v[96:99]
	v_mfma_f32_16x16x32_bf16 v[84:87], v[194:197], v[226:229], v[84:87]
	v_mfma_f32_16x16x32_bf16 v[80:83], v[202:205], v[226:229], v[80:83]
	v_mfma_f32_16x16x32_bf16 v[68:71], v[194:197], v[234:237], v[68:71]
	v_mfma_f32_16x16x32_bf16 v[64:67], v[202:205], v[234:237], v[64:67]
	s_setprio 0
	s_barrier
	s_add_i32 s30, s55, s38
	v_lshl_add_u64 v[238:239], v[238:239], 0, s[12:13]
	s_mov_b32 m0, s30
	ds_read_b128 v[206:209], v176 offset:49152
	ds_read_b128 v[210:213], v176 offset:50176
	ds_read_b128 v[214:217], v176 offset:51200
	ds_read_b128 v[218:221], v176 offset:52224
	ds_read_b128 v[222:225], v176 offset:53248
	ds_read_b128 v[226:229], v176 offset:54272
	ds_read_b128 v[230:233], v176 offset:55296
	ds_read_b128 v[234:237], v176 offset:56320
	global_load_lds_dwordx4 v[238:239], off
	s_add_i32 m0, s30, 0x2000
	s_add_u32 s28, s28, 0x80080
	v_lshl_add_u64 v[238:239], v[240:241], 0, s[12:13]
	s_addc_u32 s29, s29, 0
	s_add_i32 s30, s56, s38
	global_load_lds_dwordx4 v[238:239], off
	v_lshl_add_u64 v[238:239], s[28:29], 0, v[130:131]
	s_mov_b32 m0, s30
	s_nop 0
	global_load_lds_dwordx4 v[238:239], off
	v_lshl_add_u64 v[238:239], s[28:29], 0, v[134:135]
	s_add_i32 m0, s30, 0x2000
	s_nop 0
	global_load_lds_dwordx4 v[238:239], off
	v_lshl_add_u64 v[238:239], v[242:243], 0, s[12:13]
	s_mov_b32 m0, s46
	s_nop 0
	global_load_lds_dwordx4 v[238:239], off
	v_lshl_add_u64 v[238:239], v[244:245], 0, s[12:13]
	s_mov_b32 m0, s47
	s_nop 0
	global_load_lds_dwordx4 v[238:239], off
	s_waitcnt vmcnt(8)
	s_waitcnt lgkmcnt(0)
	s_barrier
	s_setprio 1
	s_waitcnt lgkmcnt(0)
	v_mfma_f32_16x16x32_bf16 v[60:63], v[144:147], v[206:209], v[60:63]
	v_mfma_f32_16x16x32_bf16 v[56:59], v[182:185], v[206:209], v[56:59]
	v_mfma_f32_16x16x32_bf16 v[44:47], v[144:147], v[214:217], v[44:47]
	v_mfma_f32_16x16x32_bf16 v[40:43], v[182:185], v[214:217], v[40:43]
	v_mfma_f32_16x16x32_bf16 v[28:31], v[144:147], v[222:225], v[28:31]
	v_mfma_f32_16x16x32_bf16 v[24:27], v[182:185], v[222:225], v[24:27]
	v_mfma_f32_16x16x32_bf16 v[12:15], v[144:147], v[230:233], v[12:15]
	v_mfma_f32_16x16x32_bf16 v[8:11], v[182:185], v[230:233], v[8:11]
	v_mfma_f32_16x16x32_bf16 v[60:63], v[178:181], v[210:213], v[60:63]
	v_mfma_f32_16x16x32_bf16 v[56:59], v[186:189], v[210:213], v[56:59]
	v_mfma_f32_16x16x32_bf16 v[44:47], v[178:181], v[218:221], v[44:47]
	v_mfma_f32_16x16x32_bf16 v[40:43], v[186:189], v[218:221], v[40:43]
	v_mfma_f32_16x16x32_bf16 v[28:31], v[178:181], v[226:229], v[28:31]
	v_mfma_f32_16x16x32_bf16 v[24:27], v[186:189], v[226:229], v[24:27]
	v_mfma_f32_16x16x32_bf16 v[12:15], v[178:181], v[234:237], v[12:15]
	v_mfma_f32_16x16x32_bf16 v[8:11], v[186:189], v[234:237], v[8:11]
	s_setprio 0
	s_setprio 1
	v_mfma_f32_16x16x32_bf16 v[52:55], v[190:193], v[206:209], v[52:55]
	v_mfma_f32_16x16x32_bf16 v[48:51], v[198:201], v[206:209], v[48:51]
	v_mfma_f32_16x16x32_bf16 v[36:39], v[190:193], v[214:217], v[36:39]
	v_mfma_f32_16x16x32_bf16 v[32:35], v[198:201], v[214:217], v[32:35]
	v_mfma_f32_16x16x32_bf16 v[20:23], v[190:193], v[222:225], v[20:23]
	v_mfma_f32_16x16x32_bf16 v[16:19], v[198:201], v[222:225], v[16:19]
	v_mfma_f32_16x16x32_bf16 v[4:7], v[190:193], v[230:233], v[4:7]
	v_mfma_f32_16x16x32_bf16 v[0:3], v[198:201], v[230:233], v[0:3]
	v_mfma_f32_16x16x32_bf16 v[52:55], v[194:197], v[210:213], v[52:55]
	v_mfma_f32_16x16x32_bf16 v[48:51], v[202:205], v[210:213], v[48:51]
	v_mfma_f32_16x16x32_bf16 v[36:39], v[194:197], v[218:221], v[36:39]
	v_mfma_f32_16x16x32_bf16 v[32:35], v[202:205], v[218:221], v[32:35]
	v_mfma_f32_16x16x32_bf16 v[20:23], v[194:197], v[226:229], v[20:23]
	v_mfma_f32_16x16x32_bf16 v[16:19], v[202:205], v[226:229], v[16:19]
	v_mfma_f32_16x16x32_bf16 v[4:7], v[194:197], v[234:237], v[4:7]
	v_mfma_f32_16x16x32_bf16 v[0:3], v[202:205], v[234:237], v[0:3]
	s_setprio 0
	s_barrier
	s_add_i32 s54, s54, 2
	s_add_u32 s26, s26, 0x100
	s_addc_u32 s27, s27, 0
	s_add_u32 s52, s52, 0x100
	s_addc_u32 s53, s53, 0
	s_cmp_gt_u32 s54, 29
	s_cbranch_scc0 .LBB0_884
	s_branch .Lpeel_after_p3

.Lpeel_after_p3:
	s_and_b64 vcc, exec, s[14:15]
	s_cbranch_vccz .LBB0_887
	s_barrier

.LBB0_1021:
	s_ashr_i32 s17, s16, 31
	s_lshl_b64 s[18:19], s[16:17], 20
	s_add_u32 s18, s33, s18
	s_addc_u32 s19, s34, s19
	s_and_b64 s[20:21], s[2:3], exec
	s_cselect_b32 s17, s19, s5
	s_cselect_b32 s52, s18, s4
	s_ashr_i32 s15, s14, 31
	s_lshl_b64 s[20:21], s[14:15], 20
	s_add_u32 s20, s37, s20
	s_addc_u32 s21, s38, s21
	s_and_b64 s[28:29], s[2:3], exec
	s_cselect_b32 s15, s21, s27
	s_cselect_b32 s53, s20, s26
	s_ashr_i32 s23, s22, 31
	s_lshl_b64 s[28:29], s[22:23], 13
	s_add_u32 s23, s26, 0x100
	v_lshl_add_u64 v[120:121], v[148:149], 0, s[28:29]
	v_lshl_add_u64 v[122:123], s[4:5], 0, v[150:151]
	v_lshl_add_u64 v[124:125], s[4:5], 0, v[152:153]
	s_addc_u32 s54, s27, 0
	s_mov_b32 s55, -2
	s_mov_b64 s[26:27], 0
	s_branch .Lpeel_p4

.Lpeel_p4:
	v_add_u32_e32 v126, s48, v160
	ds_read_b128 v[154:157], v126
	ds_read_b128 v[188:191], v126 offset:1024
	ds_read_b128 v[192:195], v126 offset:2048
	ds_read_b128 v[196:199], v126 offset:3072
	v_add_u32_e32 v126, s49, v160
	s_add_u32 s28, s4, s26
	ds_read_b128 v[200:203], v126
	ds_read_b128 v[204:207], v126 offset:1024
	ds_read_b128 v[208:211], v126 offset:2048
	ds_read_b128 v[212:215], v126 offset:3072
	s_addc_u32 s29, s5, s27
	s_add_u32 s28, s28, 0x100
	s_addc_u32 s29, s29, 0
	s_add_u32 s56, s23, s26
	s_addc_u32 s57, s54, s27
	s_cmpk_eq_i32 s26, 0xf00
	s_cselect_b32 s31, s17, s29
	s_cselect_b32 s30, s52, s28
	s_cselect_b32 s29, s15, s57
	s_cselect_b32 s28, s53, s56
	v_lshl_add_u64 v[126:127], v[122:123], 0, s[26:27]
	s_add_i32 m0, s25, 0xc000
	ds_read_b128 v[216:219], v178
	ds_read_b128 v[220:223], v178 offset:1024
	ds_read_b128 v[224:227], v178 offset:2048
	ds_read_b128 v[228:231], v178 offset:3072
	ds_read_b128 v[232:235], v178 offset:4096
	ds_read_b128 v[236:239], v178 offset:5120
	ds_read_b128 v[240:243], v178 offset:6144
	ds_read_b128 v[244:247], v178 offset:7168
	global_load_lds_dwordx4 v[126:127], off
	v_lshl_add_u64 v[126:127], v[124:125], 0, s[26:27]
	s_add_i32 m0, s25, 0xe000
	s_nop 0
	global_load_lds_dwordx4 v[126:127], off
	s_waitcnt vmcnt(8)
	s_waitcnt lgkmcnt(0)
	s_barrier
	s_setprio 1
	s_waitcnt lgkmcnt(0)
	v_mfma_f32_16x16x32_bf16 v[116:119], v[154:157], v[216:219], 0
	v_mfma_f32_16x16x32_bf16 v[108:111], v[192:195], v[216:219], 0
	v_mfma_f32_16x16x32_bf16 v[112:115], v[154:157], v[224:227], 0
	v_mfma_f32_16x16x32_bf16 v[92:95], v[192:195], v[224:227], 0
	v_mfma_f32_16x16x32_bf16 v[96:99], v[154:157], v[232:235], 0
	v_mfma_f32_16x16x32_bf16 v[76:79], v[192:195], v[232:235], 0
	v_mfma_f32_16x16x32_bf16 v[80:83], v[154:157], v[240:243], 0
	v_mfma_f32_16x16x32_bf16 v[64:67], v[192:195], v[240:243], 0
	v_mfma_f32_16x16x32_bf16 v[116:119], v[188:191], v[220:223], v[116:119]
	v_mfma_f32_16x16x32_bf16 v[108:111], v[196:199], v[220:223], v[108:111]
	v_mfma_f32_16x16x32_bf16 v[112:115], v[188:191], v[228:231], v[112:115]
	v_mfma_f32_16x16x32_bf16 v[92:95], v[196:199], v[228:231], v[92:95]
	v_mfma_f32_16x16x32_bf16 v[96:99], v[188:191], v[236:239], v[96:99]
	v_mfma_f32_16x16x32_bf16 v[76:79], v[196:199], v[236:239], v[76:79]
	v_mfma_f32_16x16x32_bf16 v[80:83], v[188:191], v[244:247], v[80:83]
	v_mfma_f32_16x16x32_bf16 v[64:67], v[196:199], v[244:247], v[64:67]
	s_setprio 0
	s_setprio 1
	v_mfma_f32_16x16x32_bf16 v[104:107], v[200:203], v[216:219], 0
	v_mfma_f32_16x16x32_bf16 v[100:103], v[208:211], v[216:219], 0
	v_mfma_f32_16x16x32_bf16 v[88:91], v[200:203], v[224:227], 0
	v_mfma_f32_16x16x32_bf16 v[84:87], v[208:211], v[224:227], 0
	v_mfma_f32_16x16x32_bf16 v[72:75], v[200:203], v[232:235], 0
	v_mfma_f32_16x16x32_bf16 v[68:71], v[208:211], v[232:235], 0
	v_mfma_f32_16x16x32_bf16 v[60:63], v[200:203], v[240:243], 0
	v_mfma_f32_16x16x32_bf16 v[56:59], v[208:211], v[240:243], 0
	v_mfma_f32_16x16x32_bf16 v[104:107], v[204:207], v[220:223], v[104:107]
	v_mfma_f32_16x16x32_bf16 v[100:103], v[212:215], v[220:223], v[100:103]
	v_mfma_f32_16x16x32_bf16 v[88:91], v[204:207], v[228:231], v[88:91]
	v_mfma_f32_16x16x32_bf16 v[84:87], v[212:215], v[228:231], v[84:87]
	v_mfma_f32_16x16x32_bf16 v[72:75], v[204:207], v[236:239], v[72:75]
	v_mfma_f32_16x16x32_bf16 v[68:71], v[212:215], v[236:239], v[68:71]
	v_mfma_f32_16x16x32_bf16 v[60:63], v[204:207], v[244:247], v[60:63]
	v_mfma_f32_16x16x32_bf16 v[56:59], v[212:215], v[244:247], v[56:59]
	s_setprio 0
	s_barrier
	s_add_i32 s56, s48, s36
	v_lshl_add_u64 v[158:159], s[28:29], 0, v[138:139]
	s_mov_b32 m0, s56
	ds_read_b128 v[216:219], v178 offset:16384
	ds_read_b128 v[220:223], v178 offset:17408
	ds_read_b128 v[224:227], v178 offset:18432
	ds_read_b128 v[228:231], v178 offset:19456
	ds_read_b128 v[232:235], v178 offset:20480
	ds_read_b128 v[236:239], v178 offset:21504
	ds_read_b128 v[240:243], v178 offset:22528
	ds_read_b128 v[244:247], v178 offset:23552
	global_load_lds_dwordx4 v[158:159], off
	s_add_i32 m0, s56, 0x2000
	s_add_u32 s56, s28, 0x80000
	v_lshl_add_u64 v[248:249], s[28:29], 0, v[142:143]
	s_addc_u32 s57, s29, 0
	s_add_i32 s58, s49, s36
	global_load_lds_dwordx4 v[248:249], off
	v_lshl_add_u64 v[126:127], s[56:57], 0, v[138:139]
	s_mov_b32 m0, s58
	v_lshl_add_u64 v[250:251], s[30:31], 0, v[136:137]
	global_load_lds_dwordx4 v[126:127], off
	v_lshl_add_u64 v[126:127], s[56:57], 0, v[142:143]
	s_add_i32 m0, s58, 0x2000
	v_lshl_add_u64 v[252:253], s[30:31], 0, v[140:141]
	global_load_lds_dwordx4 v[126:127], off
	s_mov_b32 m0, s25
	s_nop 0
	global_load_lds_dwordx4 v[250:251], off
	s_mov_b32 m0, s39
	s_nop 0
	global_load_lds_dwordx4 v[252:253], off
	s_waitcnt vmcnt(8)
	s_waitcnt lgkmcnt(0)
	s_barrier
	s_setprio 1
	s_waitcnt lgkmcnt(0)
	v_mfma_f32_16x16x32_bf16 v[52:55], v[154:157], v[216:219], 0
	v_mfma_f32_16x16x32_bf16 v[44:47], v[192:195], v[216:219], 0
	v_mfma_f32_16x16x32_bf16 v[48:51], v[154:157], v[224:227], 0
	v_mfma_f32_16x16x32_bf16 v[28:31], v[192:195], v[224:227], 0
	v_mfma_f32_16x16x32_bf16 v[32:35], v[154:157], v[232:235], 0
	v_mfma_f32_16x16x32_bf16 v[16:19], v[192:195], v[232:235], 0
	v_mfma_f32_16x16x32_bf16 v[132:135], v[154:157], v[240:243], 0
	v_mfma_f32_16x16x32_bf16 v[126:129], v[192:195], v[240:243], 0
	v_mfma_f32_16x16x32_bf16 v[52:55], v[188:191], v[220:223], v[52:55]
	v_mfma_f32_16x16x32_bf16 v[44:47], v[196:199], v[220:223], v[44:47]
	v_mfma_f32_16x16x32_bf16 v[48:51], v[188:191], v[228:231], v[48:51]
	v_mfma_f32_16x16x32_bf16 v[28:31], v[196:199], v[228:231], v[28:31]
	v_mfma_f32_16x16x32_bf16 v[32:35], v[188:191], v[236:239], v[32:35]
	v_mfma_f32_16x16x32_bf16 v[16:19], v[196:199], v[236:239], v[16:19]
	v_mfma_f32_16x16x32_bf16 v[132:135], v[188:191], v[244:247], v[132:135]
	v_mfma_f32_16x16x32_bf16 v[126:129], v[196:199], v[244:247], v[126:129]
	s_setprio 0
	s_setprio 1
	v_mfma_f32_16x16x32_bf16 v[40:43], v[200:203], v[216:219], 0
	v_mfma_f32_16x16x32_bf16 v[36:39], v[208:211], v[216:219], 0
	v_mfma_f32_16x16x32_bf16 v[24:27], v[200:203], v[224:227], 0
	v_mfma_f32_16x16x32_bf16 v[20:23], v[208:211], v[224:227], 0
	v_mfma_f32_16x16x32_bf16 v[12:15], v[200:203], v[232:235], 0
	v_mfma_f32_16x16x32_bf16 v[8:11], v[208:211], v[232:235], 0
	v_mfma_f32_16x16x32_bf16 v[0:3], v[200:203], v[240:243], 0
	v_mfma_f32_16x16x32_bf16 v[4:7], v[208:211], v[240:243], 0
	v_mfma_f32_16x16x32_bf16 v[40:43], v[204:207], v[220:223], v[40:43]
	v_mfma_f32_16x16x32_bf16 v[36:39], v[212:215], v[220:223], v[36:39]
	v_mfma_f32_16x16x32_bf16 v[24:27], v[204:207], v[228:231], v[24:27]
	v_mfma_f32_16x16x32_bf16 v[20:23], v[212:215], v[228:231], v[20:23]
	v_mfma_f32_16x16x32_bf16 v[12:15], v[204:207], v[236:239], v[12:15]
	v_mfma_f32_16x16x32_bf16 v[8:11], v[212:215], v[236:239], v[8:11]
	v_mfma_f32_16x16x32_bf16 v[0:3], v[204:207], v[244:247], v[0:3]
	v_mfma_f32_16x16x32_bf16 v[4:7], v[212:215], v[244:247], v[4:7]
	s_setprio 0
	s_barrier
	s_add_i32 s56, 0, 0x18000
	v_add_u32_e32 v130, s56, v160
	s_add_i32 s57, 0, 0x1c000
	ds_read_b128 v[154:157], v130
	ds_read_b128 v[188:191], v130 offset:1024
	ds_read_b128 v[192:195], v130 offset:2048
	ds_read_b128 v[196:199], v130 offset:3072
	v_add_u32_e32 v130, s57, v160
	ds_read_b128 v[200:203], v130
	ds_read_b128 v[204:207], v130 offset:1024
	ds_read_b128 v[208:211], v130 offset:2048
	ds_read_b128 v[212:215], v130 offset:3072
	s_add_u32 s30, s30, 0x80000
	s_addc_u32 s31, s31, 0
	s_mov_b32 m0, s40
	v_lshl_add_u64 v[130:131], s[30:31], 0, v[136:137]
	ds_read_b128 v[216:219], v178 offset:32768
	ds_read_b128 v[220:223], v178 offset:33792
	ds_read_b128 v[224:227], v178 offset:34816
	ds_read_b128 v[228:231], v178 offset:35840
	ds_read_b128 v[232:235], v178 offset:36864
	ds_read_b128 v[236:239], v178 offset:37888
	ds_read_b128 v[240:243], v178 offset:38912
	ds_read_b128 v[244:247], v178 offset:39936
	global_load_lds_dwordx4 v[130:131], off
	v_lshl_add_u64 v[130:131], s[30:31], 0, v[140:141]
	s_mov_b32 m0, s41
	s_nop 0
	global_load_lds_dwordx4 v[130:131], off
	s_waitcnt vmcnt(8)
	s_waitcnt lgkmcnt(0)
	s_barrier
	s_setprio 1
	s_waitcnt lgkmcnt(0)
	v_mfma_f32_16x16x32_bf16 v[116:119], v[154:157], v[216:219], v[116:119]
	v_mfma_f32_16x16x32_bf16 v[108:111], v[192:195], v[216:219], v[108:111]
	v_mfma_f32_16x16x32_bf16 v[112:115], v[154:157], v[224:227], v[112:115]
	v_mfma_f32_16x16x32_bf16 v[92:95], v[192:195], v[224:227], v[92:95]
	v_mfma_f32_16x16x32_bf16 v[96:99], v[154:157], v[232:235], v[96:99]
	v_mfma_f32_16x16x32_bf16 v[76:79], v[192:195], v[232:235], v[76:79]
	v_mfma_f32_16x16x32_bf16 v[80:83], v[154:157], v[240:243], v[80:83]
	v_mfma_f32_16x16x32_bf16 v[64:67], v[192:195], v[240:243], v[64:67]
	v_mfma_f32_16x16x32_bf16 v[116:119], v[188:191], v[220:223], v[116:119]
	v_mfma_f32_16x16x32_bf16 v[108:111], v[196:199], v[220:223], v[108:111]
	v_mfma_f32_16x16x32_bf16 v[112:115], v[188:191], v[228:231], v[112:115]
	v_mfma_f32_16x16x32_bf16 v[92:95], v[196:199], v[228:231], v[92:95]
	v_mfma_f32_16x16x32_bf16 v[96:99], v[188:191], v[236:239], v[96:99]
	v_mfma_f32_16x16x32_bf16 v[76:79], v[196:199], v[236:239], v[76:79]
	v_mfma_f32_16x16x32_bf16 v[80:83], v[188:191], v[244:247], v[80:83]
	v_mfma_f32_16x16x32_bf16 v[64:67], v[196:199], v[244:247], v[64:67]
	s_setprio 0
	s_setprio 1
	v_mfma_f32_16x16x32_bf16 v[104:107], v[200:203], v[216:219], v[104:107]
	v_mfma_f32_16x16x32_bf16 v[100:103], v[208:211], v[216:219], v[100:103]
	v_mfma_f32_16x16x32_bf16 v[88:91], v[200:203], v[224:227], v[88:91]
	v_mfma_f32_16x16x32_bf16 v[84:87], v[208:211], v[224:227], v[84:87]
	v_mfma_f32_16x16x32_bf16 v[72:75], v[200:203], v[232:235], v[72:75]
	v_mfma_f32_16x16x32_bf16 v[68:71], v[208:211], v[232:235], v[68:71]
	v_mfma_f32_16x16x32_bf16 v[60:63], v[200:203], v[240:243], v[60:63]
	v_mfma_f32_16x16x32_bf16 v[56:59], v[208:211], v[240:243], v[56:59]
	v_mfma_f32_16x16x32_bf16 v[104:107], v[204:207], v[220:223], v[104:107]
	v_mfma_f32_16x16x32_bf16 v[100:103], v[212:215], v[220:223], v[100:103]
	v_mfma_f32_16x16x32_bf16 v[88:91], v[204:207], v[228:231], v[88:91]
	v_mfma_f32_16x16x32_bf16 v[84:87], v[212:215], v[228:231], v[84:87]
	v_mfma_f32_16x16x32_bf16 v[72:75], v[204:207], v[236:239], v[72:75]
	v_mfma_f32_16x16x32_bf16 v[68:71], v[212:215], v[236:239], v[68:71]
	v_mfma_f32_16x16x32_bf16 v[60:63], v[204:207], v[244:247], v[60:63]
	v_mfma_f32_16x16x32_bf16 v[56:59], v[212:215], v[244:247], v[56:59]
	s_setprio 0
	s_barrier
	s_add_i32 s30, s56, s36
	v_lshl_add_u64 v[130:131], v[158:159], 0, s[10:11]
	s_mov_b32 m0, s30
	ds_read_b128 v[216:219], v178 offset:49152
	ds_read_b128 v[220:223], v178 offset:50176
	ds_read_b128 v[224:227], v178 offset:51200
	ds_read_b128 v[228:231], v178 offset:52224
	ds_read_b128 v[232:235], v178 offset:53248
	ds_read_b128 v[236:239], v178 offset:54272
	ds_read_b128 v[240:243], v178 offset:55296
	ds_read_b128 v[244:247], v178 offset:56320
	global_load_lds_dwordx4 v[130:131], off
	s_add_i32 m0, s30, 0x2000
	s_add_u32 s28, s28, 0x80080
	v_lshl_add_u64 v[130:131], v[248:249], 0, s[10:11]
	s_addc_u32 s29, s29, 0
	s_add_i32 s30, s57, s36
	global_load_lds_dwordx4 v[130:131], off
	v_lshl_add_u64 v[130:131], s[28:29], 0, v[138:139]
	s_mov_b32 m0, s30
	s_nop 0
	global_load_lds_dwordx4 v[130:131], off
	v_lshl_add_u64 v[130:131], s[28:29], 0, v[142:143]
	s_add_i32 m0, s30, 0x2000
	s_nop 0
	global_load_lds_dwordx4 v[130:131], off
	v_lshl_add_u64 v[130:131], v[250:251], 0, s[10:11]
	s_mov_b32 m0, s44
	s_nop 0
	global_load_lds_dwordx4 v[130:131], off
	v_lshl_add_u64 v[130:131], v[252:253], 0, s[10:11]
	s_mov_b32 m0, s45
	s_nop 0
	global_load_lds_dwordx4 v[130:131], off
	s_waitcnt vmcnt(8)
	s_waitcnt lgkmcnt(0)
	s_barrier
	s_setprio 1
	s_waitcnt lgkmcnt(0)
	v_mfma_f32_16x16x32_bf16 v[52:55], v[154:157], v[216:219], v[52:55]
	v_mfma_f32_16x16x32_bf16 v[44:47], v[192:195], v[216:219], v[44:47]
	v_mfma_f32_16x16x32_bf16 v[48:51], v[154:157], v[224:227], v[48:51]
	v_mfma_f32_16x16x32_bf16 v[28:31], v[192:195], v[224:227], v[28:31]
	v_mfma_f32_16x16x32_bf16 v[32:35], v[154:157], v[232:235], v[32:35]
	v_mfma_f32_16x16x32_bf16 v[16:19], v[192:195], v[232:235], v[16:19]
	v_mfma_f32_16x16x32_bf16 v[130:133], v[154:157], v[240:243], v[132:135]
	v_mfma_f32_16x16x32_bf16 v[126:129], v[192:195], v[240:243], v[126:129]
	v_mfma_f32_16x16x32_bf16 v[52:55], v[188:191], v[220:223], v[52:55]
	v_mfma_f32_16x16x32_bf16 v[44:47], v[196:199], v[220:223], v[44:47]
	v_mfma_f32_16x16x32_bf16 v[48:51], v[188:191], v[228:231], v[48:51]
	v_mfma_f32_16x16x32_bf16 v[28:31], v[196:199], v[228:231], v[28:31]
	v_mfma_f32_16x16x32_bf16 v[32:35], v[188:191], v[236:239], v[32:35]
	v_mfma_f32_16x16x32_bf16 v[16:19], v[196:199], v[236:239], v[16:19]
	v_mfma_f32_16x16x32_bf16 v[132:135], v[188:191], v[244:247], v[130:133]
	v_mfma_f32_16x16x32_bf16 v[128:131], v[196:199], v[244:247], v[126:129]
	s_setprio 0
	s_setprio 1
	v_mfma_f32_16x16x32_bf16 v[40:43], v[200:203], v[216:219], v[40:43]
	v_mfma_f32_16x16x32_bf16 v[36:39], v[208:211], v[216:219], v[36:39]
	v_mfma_f32_16x16x32_bf16 v[24:27], v[200:203], v[224:227], v[24:27]
	v_mfma_f32_16x16x32_bf16 v[20:23], v[208:211], v[224:227], v[20:23]
	v_mfma_f32_16x16x32_bf16 v[12:15], v[200:203], v[232:235], v[12:15]
	v_mfma_f32_16x16x32_bf16 v[8:11], v[208:211], v[232:235], v[8:11]
	v_mfma_f32_16x16x32_bf16 v[0:3], v[200:203], v[240:243], v[0:3]
	v_mfma_f32_16x16x32_bf16 v[4:7], v[208:211], v[240:243], v[4:7]
	v_mfma_f32_16x16x32_bf16 v[40:43], v[204:207], v[220:223], v[40:43]
	v_mfma_f32_16x16x32_bf16 v[36:39], v[212:215], v[220:223], v[36:39]
	v_mfma_f32_16x16x32_bf16 v[24:27], v[204:207], v[228:231], v[24:27]
	v_mfma_f32_16x16x32_bf16 v[20:23], v[212:215], v[228:231], v[20:23]
	v_mfma_f32_16x16x32_bf16 v[12:15], v[204:207], v[236:239], v[12:15]
	v_mfma_f32_16x16x32_bf16 v[8:11], v[212:215], v[236:239], v[8:11]
	v_mfma_f32_16x16x32_bf16 v[0:3], v[204:207], v[244:247], v[0:3]
	v_mfma_f32_16x16x32_bf16 v[4:7], v[212:215], v[244:247], v[4:7]
	s_setprio 0
	s_barrier
	s_add_i32 s55, s55, 2
	s_add_u32 s26, s26, 0x100
	s_addc_u32 s27, s27, 0
	s_cmp_gt_u32 s55, 29
	s_cbranch_scc1 .LBB0_1025
	s_branch .LBB0_1023
	s_nop 0

.LBB0_1467:
	s_ashr_i32 s13, s12, 31
	s_lshl_b64 s[14:15], s[12:13], 20
	s_add_u32 s14, s27, s14
	s_addc_u32 s15, s28, s15
	s_and_b64 s[16:17], s[0:1], exec
	s_cselect_b32 s13, s15, s21
	s_cselect_b32 s43, s14, s20
	s_ashr_i32 s11, s10, 31
	s_lshl_b64 s[16:17], s[10:11], 20
	s_add_u32 s16, s29, s16
	s_addc_u32 s17, s30, s17
	s_and_b64 s[24:25], s[0:1], exec
	s_cselect_b32 s11, s17, s23
	s_cselect_b32 s44, s16, s22
	s_add_u32 s20, s20, 0x80080
	s_addc_u32 s21, s21, 0
	s_add_u32 s45, s22, 0x100
	s_addc_u32 s46, s23, 0
	s_mov_b32 s47, -2
	ds_read_b128 v[144:147], v151
	ds_read_b128 v[154:157], v151 offset:1024
	ds_read_b128 v[158:161], v151 offset:2048
	ds_read_b128 v[162:165], v151 offset:3072
	ds_read_b128 v[166:169], v152
	ds_read_b128 v[170:173], v152 offset:1024
	ds_read_b128 v[174:177], v152 offset:2048
	ds_read_b128 v[178:181], v152 offset:3072
	s_add_u32 s22, s20, 0xfff80080
	s_addc_u32 s23, s21, -1
	s_cmp_eq_u32 s47, 28
	s_cselect_b32 s25, s13, s23
	s_cselect_b32 s24, s43, s22
	s_cselect_b32 s23, s11, s46
	s_cselect_b32 s22, s44, s45
	v_lshl_add_u64 v[214:215], s[20:21], 0, v[136:137]
	s_add_i32 m0, s19, 0xc000
	ds_read_b128 v[182:185], v153
	ds_read_b128 v[186:189], v153 offset:1024
	ds_read_b128 v[190:193], v153 offset:2048
	ds_read_b128 v[194:197], v153 offset:3072
	ds_read_b128 v[198:201], v153 offset:4096
	ds_read_b128 v[202:205], v153 offset:5120
	ds_read_b128 v[206:209], v153 offset:6144
	ds_read_b128 v[210:213], v153 offset:7168
	global_load_lds_dwordx4 v[214:215], off
	v_lshl_add_u64 v[214:215], s[20:21], 0, v[138:139]
	s_add_i32 m0, s19, 0xe000
	s_nop 0
	global_load_lds_dwordx4 v[214:215], off
	s_waitcnt vmcnt(8)
	s_waitcnt lgkmcnt(0)
	s_barrier
	s_setprio 1
	s_waitcnt lgkmcnt(0)
	v_mfma_f32_16x16x32_bf16 v[124:127], v[144:147], v[182:185], 0
	v_mfma_f32_16x16x32_bf16 v[120:123], v[158:161], v[182:185], 0
	v_mfma_f32_16x16x32_bf16 v[108:111], v[144:147], v[190:193], 0
	v_mfma_f32_16x16x32_bf16 v[104:107], v[158:161], v[190:193], 0
	v_mfma_f32_16x16x32_bf16 v[92:95], v[144:147], v[198:201], 0
	v_mfma_f32_16x16x32_bf16 v[88:91], v[158:161], v[198:201], 0
	v_mfma_f32_16x16x32_bf16 v[76:79], v[144:147], v[206:209], 0
	v_mfma_f32_16x16x32_bf16 v[72:75], v[158:161], v[206:209], 0
	v_mfma_f32_16x16x32_bf16 v[124:127], v[154:157], v[186:189], v[124:127]
	v_mfma_f32_16x16x32_bf16 v[120:123], v[162:165], v[186:189], v[120:123]
	v_mfma_f32_16x16x32_bf16 v[108:111], v[154:157], v[194:197], v[108:111]
	v_mfma_f32_16x16x32_bf16 v[104:107], v[162:165], v[194:197], v[104:107]
	v_mfma_f32_16x16x32_bf16 v[92:95], v[154:157], v[202:205], v[92:95]
	v_mfma_f32_16x16x32_bf16 v[88:91], v[162:165], v[202:205], v[88:91]
	v_mfma_f32_16x16x32_bf16 v[76:79], v[154:157], v[210:213], v[76:79]
	v_mfma_f32_16x16x32_bf16 v[72:75], v[162:165], v[210:213], v[72:75]
	s_setprio 0
	s_setprio 1
	v_mfma_f32_16x16x32_bf16 v[116:119], v[166:169], v[182:185], 0
	v_mfma_f32_16x16x32_bf16 v[112:115], v[174:177], v[182:185], 0
	v_mfma_f32_16x16x32_bf16 v[100:103], v[166:169], v[190:193], 0
	v_mfma_f32_16x16x32_bf16 v[96:99], v[174:177], v[190:193], 0
	v_mfma_f32_16x16x32_bf16 v[84:87], v[166:169], v[198:201], 0
	v_mfma_f32_16x16x32_bf16 v[80:83], v[174:177], v[198:201], 0
	v_mfma_f32_16x16x32_bf16 v[68:71], v[166:169], v[206:209], 0
	v_mfma_f32_16x16x32_bf16 v[64:67], v[174:177], v[206:209], 0
	v_mfma_f32_16x16x32_bf16 v[116:119], v[170:173], v[186:189], v[116:119]
	v_mfma_f32_16x16x32_bf16 v[112:115], v[178:181], v[186:189], v[112:115]
	v_mfma_f32_16x16x32_bf16 v[100:103], v[170:173], v[194:197], v[100:103]
	v_mfma_f32_16x16x32_bf16 v[96:99], v[178:181], v[194:197], v[96:99]
	v_mfma_f32_16x16x32_bf16 v[84:87], v[170:173], v[202:205], v[84:87]
	v_mfma_f32_16x16x32_bf16 v[80:83], v[178:181], v[202:205], v[80:83]
	v_mfma_f32_16x16x32_bf16 v[68:71], v[170:173], v[210:213], v[68:71]
	v_mfma_f32_16x16x32_bf16 v[64:67], v[178:181], v[210:213], v[64:67]
	s_setprio 0
	s_barrier
	s_add_i32 s48, s40, s31
	v_lshl_add_u64 v[214:215], s[22:23], 0, v[130:131]
	s_mov_b32 m0, s48
	ds_read_b128 v[182:185], v153 offset:16384
	ds_read_b128 v[186:189], v153 offset:17408
	ds_read_b128 v[190:193], v153 offset:18432
	ds_read_b128 v[194:197], v153 offset:19456
	ds_read_b128 v[198:201], v153 offset:20480
	ds_read_b128 v[202:205], v153 offset:21504
	ds_read_b128 v[206:209], v153 offset:22528
	ds_read_b128 v[210:213], v153 offset:23552
	global_load_lds_dwordx4 v[214:215], off
	s_add_i32 m0, s48, 0x2000
	s_add_u32 s48, s22, 0x80000
	v_lshl_add_u64 v[216:217], s[22:23], 0, v[134:135]
	s_addc_u32 s49, s23, 0
	s_add_i32 s50, s41, s31
	global_load_lds_dwordx4 v[216:217], off
	v_lshl_add_u64 v[218:219], s[48:49], 0, v[130:131]
	s_mov_b32 m0, s50
	v_lshl_add_u64 v[220:221], s[24:25], 0, v[132:133]
	global_load_lds_dwordx4 v[218:219], off
	v_lshl_add_u64 v[218:219], s[48:49], 0, v[134:135]
	s_add_i32 m0, s50, 0x2000
	s_nop 0
	global_load_lds_dwordx4 v[218:219], off
	v_lshl_add_u64 v[218:219], s[24:25], 0, v[128:129]
	s_mov_b32 m0, s19
	s_nop 0
	global_load_lds_dwordx4 v[218:219], off
	s_mov_b32 m0, s33
	s_nop 0
	global_load_lds_dwordx4 v[220:221], off
	s_waitcnt vmcnt(8)
	s_waitcnt lgkmcnt(0)
	s_barrier
	s_setprio 1
	s_waitcnt lgkmcnt(0)
	v_mfma_f32_16x16x32_bf16 v[60:63], v[144:147], v[182:185], 0
	v_mfma_f32_16x16x32_bf16 v[56:59], v[158:161], v[182:185], 0
	v_mfma_f32_16x16x32_bf16 v[44:47], v[144:147], v[190:193], 0
	v_mfma_f32_16x16x32_bf16 v[40:43], v[158:161], v[190:193], 0
	v_mfma_f32_16x16x32_bf16 v[28:31], v[144:147], v[198:201], 0
	v_mfma_f32_16x16x32_bf16 v[24:27], v[158:161], v[198:201], 0
	v_mfma_f32_16x16x32_bf16 v[12:15], v[144:147], v[206:209], 0
	v_mfma_f32_16x16x32_bf16 v[8:11], v[158:161], v[206:209], 0
	v_mfma_f32_16x16x32_bf16 v[60:63], v[154:157], v[186:189], v[60:63]
	v_mfma_f32_16x16x32_bf16 v[56:59], v[162:165], v[186:189], v[56:59]
	v_mfma_f32_16x16x32_bf16 v[44:47], v[154:157], v[194:197], v[44:47]
	v_mfma_f32_16x16x32_bf16 v[40:43], v[162:165], v[194:197], v[40:43]
	v_mfma_f32_16x16x32_bf16 v[28:31], v[154:157], v[202:205], v[28:31]
	v_mfma_f32_16x16x32_bf16 v[24:27], v[162:165], v[202:205], v[24:27]
	v_mfma_f32_16x16x32_bf16 v[12:15], v[154:157], v[210:213], v[12:15]
	v_mfma_f32_16x16x32_bf16 v[8:11], v[162:165], v[210:213], v[8:11]
	s_setprio 0
	s_setprio 1
	v_mfma_f32_16x16x32_bf16 v[52:55], v[166:169], v[182:185], 0
	v_mfma_f32_16x16x32_bf16 v[48:51], v[174:177], v[182:185], 0
	v_mfma_f32_16x16x32_bf16 v[36:39], v[166:169], v[190:193], 0
	v_mfma_f32_16x16x32_bf16 v[32:35], v[174:177], v[190:193], 0
	v_mfma_f32_16x16x32_bf16 v[20:23], v[166:169], v[198:201], 0
	v_mfma_f32_16x16x32_bf16 v[16:19], v[174:177], v[198:201], 0
	v_mfma_f32_16x16x32_bf16 v[4:7], v[166:169], v[206:209], 0
	v_mfma_f32_16x16x32_bf16 v[0:3], v[174:177], v[206:209], 0
	v_mfma_f32_16x16x32_bf16 v[52:55], v[170:173], v[186:189], v[52:55]
	v_mfma_f32_16x16x32_bf16 v[48:51], v[178:181], v[186:189], v[48:51]
	v_mfma_f32_16x16x32_bf16 v[36:39], v[170:173], v[194:197], v[36:39]
	v_mfma_f32_16x16x32_bf16 v[32:35], v[178:181], v[194:197], v[32:35]
	v_mfma_f32_16x16x32_bf16 v[20:23], v[170:173], v[202:205], v[20:23]
	v_mfma_f32_16x16x32_bf16 v[16:19], v[178:181], v[202:205], v[16:19]
	v_mfma_f32_16x16x32_bf16 v[4:7], v[170:173], v[210:213], v[4:7]
	v_mfma_f32_16x16x32_bf16 v[0:3], v[178:181], v[210:213], v[0:3]
	s_setprio 0
	s_barrier
	s_add_i32 s48, 0, 0x18000
	s_add_i32 s49, 0, 0x1c000
	v_add_u32_e32 v162, s48, v149
	v_add_u32_e32 v178, s49, v149
	ds_read_b128 v[144:147], v162
	ds_read_b128 v[154:157], v162 offset:1024
	ds_read_b128 v[158:161], v162 offset:2048
	ds_read_b128 v[162:165], v162 offset:3072
	ds_read_b128 v[166:169], v178
	ds_read_b128 v[170:173], v178 offset:1024
	ds_read_b128 v[174:177], v178 offset:2048
	ds_read_b128 v[178:181], v178 offset:3072
	s_add_u32 s24, s24, 0x80000
	s_addc_u32 s25, s25, 0
	s_mov_b32 m0, s34
	v_lshl_add_u64 v[222:223], s[24:25], 0, v[128:129]
	ds_read_b128 v[182:185], v153 offset:32768
	ds_read_b128 v[186:189], v153 offset:33792
	ds_read_b128 v[190:193], v153 offset:34816
	ds_read_b128 v[194:197], v153 offset:35840
	ds_read_b128 v[198:201], v153 offset:36864
	ds_read_b128 v[202:205], v153 offset:37888
	ds_read_b128 v[206:209], v153 offset:38912
	ds_read_b128 v[210:213], v153 offset:39936
	global_load_lds_dwordx4 v[222:223], off
	v_lshl_add_u64 v[222:223], s[24:25], 0, v[132:133]
	s_mov_b32 m0, s35
	s_nop 0
	global_load_lds_dwordx4 v[222:223], off
	s_waitcnt vmcnt(8)
	s_waitcnt lgkmcnt(0)
	s_barrier
	s_setprio 1
	s_waitcnt lgkmcnt(0)
	v_mfma_f32_16x16x32_bf16 v[124:127], v[144:147], v[182:185], v[124:127]
	v_mfma_f32_16x16x32_bf16 v[120:123], v[158:161], v[182:185], v[120:123]
	v_mfma_f32_16x16x32_bf16 v[108:111], v[144:147], v[190:193], v[108:111]
	v_mfma_f32_16x16x32_bf16 v[104:107], v[158:161], v[190:193], v[104:107]
	v_mfma_f32_16x16x32_bf16 v[92:95], v[144:147], v[198:201], v[92:95]
	v_mfma_f32_16x16x32_bf16 v[88:91], v[158:161], v[198:201], v[88:91]
	v_mfma_f32_16x16x32_bf16 v[76:79], v[144:147], v[206:209], v[76:79]
	v_mfma_f32_16x16x32_bf16 v[72:75], v[158:161], v[206:209], v[72:75]
	v_mfma_f32_16x16x32_bf16 v[124:127], v[154:157], v[186:189], v[124:127]
	v_mfma_f32_16x16x32_bf16 v[120:123], v[162:165], v[186:189], v[120:123]
	v_mfma_f32_16x16x32_bf16 v[108:111], v[154:157], v[194:197], v[108:111]
	v_mfma_f32_16x16x32_bf16 v[104:107], v[162:165], v[194:197], v[104:107]
	v_mfma_f32_16x16x32_bf16 v[92:95], v[154:157], v[202:205], v[92:95]
	v_mfma_f32_16x16x32_bf16 v[88:91], v[162:165], v[202:205], v[88:91]
	v_mfma_f32_16x16x32_bf16 v[76:79], v[154:157], v[210:213], v[76:79]
	v_mfma_f32_16x16x32_bf16 v[72:75], v[162:165], v[210:213], v[72:75]
	s_setprio 0
	s_setprio 1
	v_mfma_f32_16x16x32_bf16 v[116:119], v[166:169], v[182:185], v[116:119]
	v_mfma_f32_16x16x32_bf16 v[112:115], v[174:177], v[182:185], v[112:115]
	v_mfma_f32_16x16x32_bf16 v[100:103], v[166:169], v[190:193], v[100:103]
	v_mfma_f32_16x16x32_bf16 v[96:99], v[174:177], v[190:193], v[96:99]
	v_mfma_f32_16x16x32_bf16 v[84:87], v[166:169], v[198:201], v[84:87]
	v_mfma_f32_16x16x32_bf16 v[80:83], v[174:177], v[198:201], v[80:83]
	v_mfma_f32_16x16x32_bf16 v[68:71], v[166:169], v[206:209], v[68:71]
	v_mfma_f32_16x16x32_bf16 v[64:67], v[174:177], v[206:209], v[64:67]
	v_mfma_f32_16x16x32_bf16 v[116:119], v[170:173], v[186:189], v[116:119]
	v_mfma_f32_16x16x32_bf16 v[112:115], v[178:181], v[186:189], v[112:115]
	v_mfma_f32_16x16x32_bf16 v[100:103], v[170:173], v[194:197], v[100:103]
	v_mfma_f32_16x16x32_bf16 v[96:99], v[178:181], v[194:197], v[96:99]
	v_mfma_f32_16x16x32_bf16 v[84:87], v[170:173], v[202:205], v[84:87]
	v_mfma_f32_16x16x32_bf16 v[80:83], v[178:181], v[202:205], v[80:83]
	v_mfma_f32_16x16x32_bf16 v[68:71], v[170:173], v[210:213], v[68:71]
	v_mfma_f32_16x16x32_bf16 v[64:67], v[178:181], v[210:213], v[64:67]
	s_setprio 0
	s_barrier
	s_add_i32 s24, s48, s31
	v_lshl_add_u64 v[214:215], v[214:215], 0, s[6:7]
	s_mov_b32 m0, s24
	ds_read_b128 v[182:185], v153 offset:49152
	ds_read_b128 v[186:189], v153 offset:50176
	ds_read_b128 v[190:193], v153 offset:51200
	ds_read_b128 v[194:197], v153 offset:52224
	ds_read_b128 v[198:201], v153 offset:53248
	ds_read_b128 v[202:205], v153 offset:54272
	ds_read_b128 v[206:209], v153 offset:55296
	ds_read_b128 v[210:213], v153 offset:56320
	global_load_lds_dwordx4 v[214:215], off
	s_add_i32 m0, s24, 0x2000
	s_add_u32 s22, s22, 0x80080
	v_lshl_add_u64 v[214:215], v[216:217], 0, s[6:7]
	s_addc_u32 s23, s23, 0
	s_add_i32 s24, s49, s31
	global_load_lds_dwordx4 v[214:215], off
	v_lshl_add_u64 v[214:215], s[22:23], 0, v[130:131]
	s_mov_b32 m0, s24
	s_nop 0
	global_load_lds_dwordx4 v[214:215], off
	v_lshl_add_u64 v[214:215], s[22:23], 0, v[134:135]
	s_add_i32 m0, s24, 0x2000
	s_nop 0
	global_load_lds_dwordx4 v[214:215], off
	v_lshl_add_u64 v[214:215], v[218:219], 0, s[6:7]
	s_mov_b32 m0, s37
	s_nop 0
	global_load_lds_dwordx4 v[214:215], off
	v_lshl_add_u64 v[214:215], v[220:221], 0, s[6:7]
	s_mov_b32 m0, s38
	s_nop 0
	global_load_lds_dwordx4 v[214:215], off
	s_waitcnt vmcnt(8)
	s_waitcnt lgkmcnt(0)
	s_barrier
	s_setprio 1
	s_waitcnt lgkmcnt(0)
	v_mfma_f32_16x16x32_bf16 v[60:63], v[144:147], v[182:185], v[60:63]
	v_mfma_f32_16x16x32_bf16 v[56:59], v[158:161], v[182:185], v[56:59]
	v_mfma_f32_16x16x32_bf16 v[44:47], v[144:147], v[190:193], v[44:47]
	v_mfma_f32_16x16x32_bf16 v[40:43], v[158:161], v[190:193], v[40:43]
	v_mfma_f32_16x16x32_bf16 v[28:31], v[144:147], v[198:201], v[28:31]
	v_mfma_f32_16x16x32_bf16 v[24:27], v[158:161], v[198:201], v[24:27]
	v_mfma_f32_16x16x32_bf16 v[12:15], v[144:147], v[206:209], v[12:15]
	v_mfma_f32_16x16x32_bf16 v[8:11], v[158:161], v[206:209], v[8:11]
	v_mfma_f32_16x16x32_bf16 v[60:63], v[154:157], v[186:189], v[60:63]
	v_mfma_f32_16x16x32_bf16 v[56:59], v[162:165], v[186:189], v[56:59]
	v_mfma_f32_16x16x32_bf16 v[44:47], v[154:157], v[194:197], v[44:47]
	v_mfma_f32_16x16x32_bf16 v[40:43], v[162:165], v[194:197], v[40:43]
	v_mfma_f32_16x16x32_bf16 v[28:31], v[154:157], v[202:205], v[28:31]
	v_mfma_f32_16x16x32_bf16 v[24:27], v[162:165], v[202:205], v[24:27]
	v_mfma_f32_16x16x32_bf16 v[12:15], v[154:157], v[210:213], v[12:15]
	v_mfma_f32_16x16x32_bf16 v[8:11], v[162:165], v[210:213], v[8:11]
	s_setprio 0
	s_setprio 1
	v_mfma_f32_16x16x32_bf16 v[52:55], v[166:169], v[182:185], v[52:55]
	v_mfma_f32_16x16x32_bf16 v[48:51], v[174:177], v[182:185], v[48:51]
	v_mfma_f32_16x16x32_bf16 v[36:39], v[166:169], v[190:193], v[36:39]
	v_mfma_f32_16x16x32_bf16 v[32:35], v[174:177], v[190:193], v[32:35]
	v_mfma_f32_16x16x32_bf16 v[20:23], v[166:169], v[198:201], v[20:23]
	v_mfma_f32_16x16x32_bf16 v[16:19], v[174:177], v[198:201], v[16:19]
	v_mfma_f32_16x16x32_bf16 v[4:7], v[166:169], v[206:209], v[4:7]
	v_mfma_f32_16x16x32_bf16 v[0:3], v[174:177], v[206:209], v[0:3]
	v_mfma_f32_16x16x32_bf16 v[52:55], v[170:173], v[186:189], v[52:55]
	v_mfma_f32_16x16x32_bf16 v[48:51], v[178:181], v[186:189], v[48:51]
	v_mfma_f32_16x16x32_bf16 v[36:39], v[170:173], v[194:197], v[36:39]
	v_mfma_f32_16x16x32_bf16 v[32:35], v[178:181], v[194:197], v[32:35]
	v_mfma_f32_16x16x32_bf16 v[20:23], v[170:173], v[202:205], v[20:23]
	v_mfma_f32_16x16x32_bf16 v[16:19], v[178:181], v[202:205], v[16:19]
	v_mfma_f32_16x16x32_bf16 v[4:7], v[170:173], v[210:213], v[4:7]
	v_mfma_f32_16x16x32_bf16 v[0:3], v[178:181], v[210:213], v[0:3]
	s_setprio 0
	s_barrier
	s_add_i32 s47, s47, 2
	s_add_u32 s20, s20, 0x100
	s_addc_u32 s21, s21, 0
	s_add_u32 s45, s45, 0x100
	s_addc_u32 s46, s46, 0
	s_cmp_gt_u32 s47, 29
	s_cbranch_scc0 .LBB0_1468
	s_branch .Lpeel_after_p6

.Lpeel_after_p6:
	s_and_b64 vcc, exec, s[8:9]
	s_cbranch_vccz .LBB0_1471
	s_barrier
